# MV2: attention loop: the last TWO P.V MFMA groups (8 MFMAs) moved behind the X section's closing barrier to the head of the next softmax section; on top of BE1
# speedup vs baseline: 1.0045x; 1.0045x over previous
.Lmy_attn_top:
	s_waitcnt lgkmcnt(0)
	s_barrier
	v_mfma_f32_32x32x16_bf16 v[36:51], v[148:151], v[188:191], v[36:51]
	v_mfma_f32_32x32x16_bf16 v[36:51], v[152:155], v[192:195], v[36:51]
	v_mfma_f32_32x32x16_bf16 v[36:51], v[156:159], v[196:199], v[36:51]
	v_mfma_f32_32x32x16_bf16 v[36:51], v[160:163], v[200:203], v[36:51]
	v_mfma_f32_32x32x16_bf16 v[20:35], v[148:151], v[204:207], v[20:35]
	v_mfma_f32_32x32x16_bf16 v[20:35], v[152:155], v[216:219], v[20:35]
	v_mfma_f32_32x32x16_bf16 v[20:35], v[156:159], v[220:223], v[20:35]
	v_mfma_f32_32x32x16_bf16 v[20:35], v[160:163], v[224:227], v[20:35]
	v_fma_f32 v183, v183, v184, v185

.LBB0_633:
	s_waitcnt lgkmcnt(0)
	s_barrier
	v_lshl_add_u32 v187, s53, 14, v173
	ds_read_b64_tr_b16 v[188:189], v187 offset:0
	ds_read_b64_tr_b16 v[190:191], v187 offset:0x800
	ds_read_b64_tr_b16 v[192:193], v187 offset:0x1000
	ds_read_b64_tr_b16 v[194:195], v187 offset:0x1800
	ds_read_b64_tr_b16 v[196:197], v187 offset:0x2000
	ds_read_b64_tr_b16 v[198:199], v187 offset:0x2800
	ds_read_b64_tr_b16 v[200:201], v187 offset:0x3000
	ds_read_b64_tr_b16 v[202:203], v187 offset:0x3800
	s_lshl_b32 s52, s49, 14
	v_add_u32_e32 v208, s52, v174
	ds_read_b128 v[68:71], v208 offset:0
	ds_read_b128 v[72:75], v208 offset:0x2000
	v_add_u32_e32 v209, s52, v175
	ds_read_b128 v[204:207], v209 offset:0
	ds_read_b128 v[216:219], v209 offset:0x2000
	v_add_u32_e32 v210, s52, v176
	ds_read_b128 v[220:223], v210 offset:0
	ds_read_b128 v[224:227], v210 offset:0x2000
	v_add_u32_e32 v211, s52, v177
	ds_read_b128 v[228:231], v211 offset:0
	ds_read_b128 v[232:235], v211 offset:0x2000
	s_waitcnt lgkmcnt(4)
	v_mfma_f32_32x32x16_bf16 v[84:99], v[68:71], v[128:131], 0
	v_mfma_f32_32x32x16_bf16 v[68:83], v[72:75], v[128:131], 0
	v_mfma_f32_32x32x16_bf16 v[84:99], v[204:207], v[124:127], v[84:99]
	v_mfma_f32_32x32x16_bf16 v[68:83], v[216:219], v[124:127], v[68:83]
	ds_read_b128 v[204:207], v208 offset:0x80
	ds_read_b128 v[216:219], v208 offset:0x2080
	ds_read_b128 v[236:239], v209 offset:0x80
	ds_read_b128 v[242:245], v209 offset:0x2080
	s_waitcnt lgkmcnt(4)
	v_mfma_f32_32x32x16_bf16 v[84:99], v[220:223], v[120:123], v[84:99]
	v_mfma_f32_32x32x16_bf16 v[68:83], v[224:227], v[120:123], v[68:83]
	v_mfma_f32_32x32x16_bf16 v[84:99], v[228:231], v[116:119], v[84:99]
	v_mfma_f32_32x32x16_bf16 v[68:83], v[232:235], v[116:119], v[68:83]
	ds_read_b128 v[220:223], v210 offset:0x80
	ds_read_b128 v[224:227], v210 offset:0x2080
	ds_read_b128 v[228:231], v211 offset:0x80
	ds_read_b128 v[232:235], v211 offset:0x2080
	s_waitcnt lgkmcnt(4)
	v_mfma_f32_32x32x16_bf16 v[84:99], v[204:207], v[112:115], v[84:99]
	v_mfma_f32_32x32x16_bf16 v[68:83], v[216:219], v[112:115], v[68:83]
	v_mfma_f32_32x32x16_bf16 v[84:99], v[236:239], v[108:111], v[84:99]
	v_mfma_f32_32x32x16_bf16 v[68:83], v[242:245], v[108:111], v[68:83]
	s_waitcnt lgkmcnt(0)
	v_mfma_f32_32x32x16_bf16 v[84:99], v[220:223], v[104:107], v[84:99]
	v_mfma_f32_32x32x16_bf16 v[68:83], v[224:227], v[104:107], v[68:83]
	v_mfma_f32_32x32x16_bf16 v[84:99], v[228:231], v[100:103], v[84:99]
	v_mfma_f32_32x32x16_bf16 v[68:83], v[232:235], v[100:103], v[68:83]
	ds_read_b64_tr_b16 v[204:205], v187 offset:0x200
	ds_read_b64_tr_b16 v[206:207], v187 offset:0xa00
	ds_read_b64_tr_b16 v[216:217], v187 offset:0x1200
	ds_read_b64_tr_b16 v[218:219], v187 offset:0x1a00
	ds_read_b64_tr_b16 v[220:221], v187 offset:0x2200
	ds_read_b64_tr_b16 v[222:223], v187 offset:0x2a00
	ds_read_b64_tr_b16 v[224:225], v187 offset:0x3200
	ds_read_b64_tr_b16 v[226:227], v187 offset:0x3a00
	s_waitcnt lgkmcnt(8)
	v_mfma_f32_32x32x16_bf16 v[4:19], v[148:151], v[188:191], v[4:19]
	s_lshl_b32 s19, s51, 14
	s_add_i32 s8, s19, 0
	v_add_u32_e32 v236, s8, v179
	s_waitcnt vmcnt(0)
	v_mfma_f32_32x32x16_bf16 v[4:19], v[152:155], v[192:195], v[4:19]
	ds_write_b128 v236, v[144:147]
	v_add_u32_e32 v236, s8, v178
	v_mfma_f32_32x32x16_bf16 v[4:19], v[156:159], v[196:199], v[4:19]
	ds_write_b128 v236, v[136:139]
	v_add_u32_e32 v236, s8, v180
	v_mfma_f32_32x32x16_bf16 v[4:19], v[160:163], v[200:203], v[4:19]
	ds_read_b64_tr_b16 v[188:189], v187 offset:0x400
	ds_read_b64_tr_b16 v[190:191], v187 offset:0xc00
	ds_read_b64_tr_b16 v[192:193], v187 offset:0x1400
	ds_read_b64_tr_b16 v[194:195], v187 offset:0x1c00
	ds_read_b64_tr_b16 v[196:197], v187 offset:0x2400
	ds_read_b64_tr_b16 v[198:199], v187 offset:0x2c00
	ds_read_b64_tr_b16 v[200:201], v187 offset:0x3400
	ds_read_b64_tr_b16 v[202:203], v187 offset:0x3c00
	s_waitcnt lgkmcnt(10)
	v_mfma_f32_32x32x16_bf16 v[52:67], v[148:151], v[204:207], v[52:67]
	ds_write_b128 v236, v[140:143] offset:49152
	v_add_u32_e32 v236, s8, v181
	v_mfma_f32_32x32x16_bf16 v[52:67], v[152:155], v[216:219], v[52:67]
	ds_write_b128 v236, v[132:135] offset:49152
	s_add_i32 s48, s48, 1
	v_mfma_f32_32x32x16_bf16 v[52:67], v[156:159], v[220:223], v[52:67]
	s_sub_i32 s8, s50, s47
	s_min_u32 s36, s50, s8
	s_lshl_b64 s[8:9], s[36:37], 10
	s_cmp_lt_u32 s50, s47
	s_cselect_b32 s16, s30, s20
	s_cselect_b32 s17, s31, s21
	v_mfma_f32_32x32x16_bf16 v[52:67], v[160:163], v[224:227], v[52:67]
	ds_read_b64_tr_b16 v[204:205], v187 offset:0x600
	ds_read_b64_tr_b16 v[206:207], v187 offset:0xe00
	ds_read_b64_tr_b16 v[216:217], v187 offset:0x1600
	ds_read_b64_tr_b16 v[218:219], v187 offset:0x1e00
	ds_read_b64_tr_b16 v[220:221], v187 offset:0x2600
	ds_read_b64_tr_b16 v[222:223], v187 offset:0x2e00
	ds_read_b64_tr_b16 v[224:225], v187 offset:0x3600
	ds_read_b64_tr_b16 v[226:227], v187 offset:0x3e00
	s_cselect_b32 s36, s42, s26
	s_cselect_b32 s54, s43, s27
	s_add_u32 s16, s16, s8
	s_addc_u32 s17, s17, s9
	s_add_u32 s8, s36, s8
	s_addc_u32 s9, s54, s9
	global_load_dwordx4 v[144:147], v2, s[8:9]
	s_add_u32 s8, s8, 0x8000
	s_addc_u32 s9, s9, 0
	global_load_dwordx4 v[136:139], v2, s[8:9]
	global_load_dwordx4 v[140:143], v2, s[16:17]
	s_add_u32 s16, s16, 0x8000
	s_addc_u32 s17, s17, 0
	global_load_dwordx4 v[132:135], v2, s[16:17]
	s_waitcnt lgkmcnt(0)
